# pool-fold loop in prologue: three dependent load rounds per iteration issued as one round (fresh registers), counted waits
# baseline (speedup 1.0000x reference)
.LBB0_364:
	v_add_co_u32_e32 v12, vcc, 0xffff1000, v2
	s_movk_i32 s19, 0xa000
	s_nop 0
	v_addc_co_u32_e32 v13, vcc, -1, v3, vcc
	global_load_dword v172, v[12:13], off
	v_add_co_u32_e32 v12, vcc, 0xffff2000, v2
	s_add_u32 s24, s14, s10
	s_nop 0
	v_addc_co_u32_e32 v13, vcc, -1, v3, vcc
	global_load_dword v173, v[12:13], off
	v_add_co_u32_e32 v12, vcc, 0xffff3000, v2
	s_addc_u32 s25, s15, s11
	s_nop 0
	v_addc_co_u32_e32 v13, vcc, -1, v3, vcc
	global_load_dword v174, v[12:13], off
	v_add_co_u32_e32 v12, vcc, 0xffff4000, v2
	s_nop 1
	v_addc_co_u32_e32 v13, vcc, -1, v3, vcc
	global_load_dword v175, v[12:13], off
	v_add_co_u32_e32 v12, vcc, 0xffff5000, v2
	s_nop 1
	v_addc_co_u32_e32 v13, vcc, -1, v3, vcc
	global_load_dword v22, v[12:13], off
	v_add_co_u32_e32 v12, vcc, 0xffff6000, v2
	s_nop 1
	v_addc_co_u32_e32 v13, vcc, -1, v3, vcc
	global_load_dword v23, v[12:13], off
	v_add_co_u32_e32 v12, vcc, 0xffff7000, v2
	s_nop 1
	v_addc_co_u32_e32 v13, vcc, -1, v3, vcc
	v_add_co_u32_e32 v14, vcc, 0xffff8000, v2
	global_load_dword v12, v[12:13], off
	s_nop 0
	v_addc_co_u32_e32 v15, vcc, -1, v3, vcc
	v_add_co_u32_e32 v16, vcc, s19, v2
	s_movk_i32 s19, 0xc000
	s_nop 0
	v_addc_co_u32_e32 v17, vcc, -1, v3, vcc
	v_add_co_u32_e32 v18, vcc, s19, v2
	s_movk_i32 s19, 0xe000
	s_nop 0
	v_addc_co_u32_e32 v19, vcc, -1, v3, vcc
	global_load_dword v13, v[14:15], off
	s_nop 0
	global_load_dword v14, v[16:17], off offset:-4096
	global_load_dword v15, v[16:17], off
	s_nop 0
	global_load_dword v16, v[18:19], off offset:-4096
	global_load_dword v17, v[18:19], off
	v_add_co_u32_e32 v18, vcc, s19, v2
	s_nop 1
	v_addc_co_u32_e32 v19, vcc, -1, v3, vcc
	global_load_dword v20, v[18:19], off offset:-4096
	global_load_dword v21, v[18:19], off
	s_nop 0
	global_load_dword v18, v[2:3], off offset:-4096
	global_load_dword v19, v[2:3], off
	global_load_dwordx4 v[176:179], v193, s[24:25]
	global_load_dwordx4 v[28:31], v193, s[24:25] offset:48
	global_load_dwordx4 v[32:35], v193, s[24:25] offset:32
	global_load_dwordx4 v[36:39], v193, s[24:25] offset:16
	s_add_u32 s24, s16, s10
	s_addc_u32 s25, s17, s11
	s_add_i32 s18, s18, 16
	s_add_u32 s10, s10, 64
	s_addc_u32 s11, s11, 0
	s_cmpk_lt_u32 s18, 0x70
	global_load_dwordx4 v[24:27], v193, s[24:25] offset:16
	global_load_dwordx4 v[40:43], v193, s[24:25] offset:48
	global_load_dwordx4 v[44:47], v193, s[24:25] offset:32
	global_load_dwordx4 v[48:51], v193, s[24:25]
	global_load_dwordx4 v[52:55], v193, s[24:25] offset:528
	global_load_dwordx4 v[56:59], v193, s[24:25] offset:560
	global_load_dwordx4 v[60:63], v193, s[24:25] offset:544
	global_load_dwordx4 v[64:67], v193, s[24:25] offset:512
	global_load_dwordx4 v[68:71], v193, s[24:25] offset:1040
	global_load_dwordx4 v[72:75], v193, s[24:25] offset:1072
	global_load_dwordx4 v[76:79], v193, s[24:25] offset:1056
	global_load_dwordx4 v[80:83], v193, s[24:25] offset:1024
	global_load_dwordx4 v[84:87], v193, s[24:25] offset:1552
	global_load_dwordx4 v[88:91], v193, s[24:25] offset:1584
	global_load_dwordx4 v[92:95], v193, s[24:25] offset:1568
	global_load_dwordx4 v[96:99], v193, s[24:25] offset:1536
	global_load_dwordx4 v[100:103], v193, s[24:25] offset:2064
	global_load_dwordx4 v[104:107], v193, s[24:25] offset:2096
	global_load_dwordx4 v[108:111], v193, s[24:25] offset:2080
	global_load_dwordx4 v[112:115], v193, s[24:25] offset:2048
	global_load_dwordx4 v[116:119], v193, s[24:25] offset:2576
	global_load_dwordx4 v[120:123], v193, s[24:25] offset:2608
	global_load_dwordx4 v[124:127], v193, s[24:25] offset:2592
	global_load_dwordx4 v[128:131], v193, s[24:25] offset:2560
	global_load_dwordx4 v[132:135], v193, s[24:25] offset:3120
	global_load_dwordx4 v[136:139], v193, s[24:25] offset:3104
	global_load_dwordx4 v[140:143], v193, s[24:25] offset:3088
	global_load_dwordx4 v[144:147], v193, s[24:25] offset:3072
	global_load_dwordx4 v[156:159], v193, s[24:25] offset:3632
	global_load_dwordx4 v[160:163], v193, s[24:25] offset:3616
	global_load_dwordx4 v[164:167], v193, s[24:25] offset:3600
	global_load_dwordx4 v[168:171], v193, s[24:25] offset:3584
	s_waitcnt vmcnt(35)
	v_mul_f32_e32 v148, v172, v176
	v_mul_f32_e32 v150, v173, v177
	v_mul_f32_e32 v152, v174, v178
	v_mul_f32_e32 v154, v175, v179
	s_waitcnt vmcnt(32)
	v_pk_mul_f32 v[22:23], v[22:23], v[36:37]
	v_pk_mul_f32 v[20:21], v[20:21], v[28:29]
	v_pk_mul_f32 v[18:19], v[18:19], v[30:31]
	v_pk_mul_f32 v[12:13], v[12:13], v[38:39]
	v_pk_mul_f32 v[14:15], v[14:15], v[32:33]
	v_pk_mul_f32 v[16:17], v[16:17], v[34:35]
	s_waitcnt vmcnt(28)
	v_mov_b32_e32 v36, v48
	s_waitcnt vmcnt(24)
	v_mov_b32_e32 v37, v64
	v_pk_fma_f32 v[4:5], v[148:149], v[36:37], v[4:5] op_sel_hi:[0,1,1]
	v_mov_b32_e32 v64, v49
	v_pk_fma_f32 v[4:5], v[150:151], v[64:65], v[4:5] op_sel_hi:[0,1,1]
	v_mov_b32_e32 v36, v50
	v_mov_b32_e32 v37, v66
	v_pk_fma_f32 v[4:5], v[152:153], v[36:37], v[4:5] op_sel_hi:[0,1,1]
	v_mov_b32_e32 v66, v51
	v_pk_fma_f32 v[4:5], v[154:155], v[66:67], v[4:5] op_sel_hi:[0,1,1]
	v_mov_b32_e32 v36, v24
	v_mov_b32_e32 v37, v52
	v_pk_fma_f32 v[36:37], v[22:23], v[36:37], v[4:5] op_sel_hi:[0,1,1]
	s_waitcnt vmcnt(20)
	v_mov_b32_e32 v4, v80
	s_waitcnt vmcnt(16)
	v_mov_b32_e32 v5, v96
	v_pk_fma_f32 v[4:5], v[148:149], v[4:5], v[6:7] op_sel_hi:[0,1,1]
	v_mov_b32_e32 v96, v81
	v_pk_fma_f32 v[4:5], v[150:151], v[96:97], v[4:5] op_sel_hi:[0,1,1]
	v_mov_b32_e32 v6, v82
	v_mov_b32_e32 v7, v98
	v_pk_fma_f32 v[4:5], v[152:153], v[6:7], v[4:5] op_sel_hi:[0,1,1]
	v_mov_b32_e32 v98, v83
	v_pk_fma_f32 v[4:5], v[154:155], v[98:99], v[4:5] op_sel_hi:[0,1,1]
	v_mov_b32_e32 v6, v68
	v_mov_b32_e32 v7, v84
	v_pk_fma_f32 v[96:97], v[22:23], v[6:7], v[4:5] op_sel_hi:[0,1,1]
	s_waitcnt vmcnt(12)
	v_mov_b32_e32 v4, v112
	s_waitcnt vmcnt(8)
	v_mov_b32_e32 v5, v128
	v_pk_fma_f32 v[4:5], v[148:149], v[4:5], v[10:11] op_sel_hi:[0,1,1]
	v_mov_b32_e32 v128, v113
	v_pk_fma_f32 v[4:5], v[150:151], v[128:129], v[4:5] op_sel_hi:[0,1,1]
	v_mov_b32_e32 v6, v114
	v_mov_b32_e32 v7, v130
	v_pk_fma_f32 v[4:5], v[152:153], v[6:7], v[4:5] op_sel_hi:[0,1,1]
	v_mov_b32_e32 v130, v115
	v_pk_fma_f32 v[4:5], v[154:155], v[130:131], v[4:5] op_sel_hi:[0,1,1]
	v_mov_b32_e32 v6, v100
	v_mov_b32_e32 v7, v116
	v_pk_fma_f32 v[10:11], v[22:23], v[6:7], v[4:5] op_sel_hi:[0,1,1]
	s_waitcnt vmcnt(4)
	v_mov_b32_e32 v112, v144
	v_mov_b32_e32 v52, v25
	v_mov_b32_e32 v116, v101
	v_mul_f32_e32 v98, v22, v140
	v_mov_b32_e32 v84, v69
	v_mul_f32_e32 v24, v12, v142
	v_pk_fma_f32 v[10:11], v[22:23], v[116:117], v[10:11] op_sel:[1,0,0]
	v_mul_f32_e32 v32, v14, v136
	v_mul_f32_e32 v68, v15, v137
	v_mul_f32_e32 v34, v16, v138
	v_mul_f32_e32 v28, v20, v132
	v_mul_f32_e32 v30, v18, v134
	s_mov_b64 s[24:25], 0x10000
	v_lshl_add_u64 v[2:3], v[2:3], 0, s[24:25]
	s_waitcnt vmcnt(3)
	v_pk_mul_f32 v[100:101], v[18:19], v[158:159]
	v_mov_b32_e32 v6, v26
	v_mov_b32_e32 v7, v54
	s_waitcnt vmcnt(0)
	v_mov_b32_e32 v113, v168
	v_pk_fma_f32 v[8:9], v[148:149], v[112:113], v[8:9] op_sel_hi:[0,1,1]
	v_mov_b32_e32 v168, v145
	v_pk_fma_f32 v[8:9], v[150:151], v[168:169], v[8:9] op_sel_hi:[0,1,1]
	v_mov_b32_e32 v168, v146
	v_mov_b32_e32 v169, v170
	v_pk_fma_f32 v[8:9], v[152:153], v[168:169], v[8:9] op_sel_hi:[0,1,1]
	v_mov_b32_e32 v170, v147
	v_pk_fma_f32 v[8:9], v[154:155], v[170:171], v[8:9] op_sel_hi:[0,1,1]
	v_pk_mul_f32 v[170:171], v[20:21], v[156:157]
	v_pk_fma_f32 v[4:5], v[22:23], v[52:53], v[36:37] op_sel:[1,0,0]
	v_mov_b32_e32 v54, v27
	v_pk_fma_f32 v[4:5], v[12:13], v[6:7], v[4:5] op_sel_hi:[0,1,1]
	v_pk_fma_f32 v[4:5], v[12:13], v[54:55], v[4:5] op_sel:[1,0,0]
	v_mov_b32_e32 v6, v44
	v_mov_b32_e32 v7, v60
	v_pk_fma_f32 v[4:5], v[14:15], v[6:7], v[4:5] op_sel_hi:[0,1,1]
	v_mov_b32_e32 v60, v45
	v_pk_fma_f32 v[4:5], v[14:15], v[60:61], v[4:5] op_sel:[1,0,0]
	v_mov_b32_e32 v6, v46
	v_mov_b32_e32 v7, v62
	v_pk_fma_f32 v[4:5], v[16:17], v[6:7], v[4:5] op_sel_hi:[0,1,1]
	v_mov_b32_e32 v62, v47
	v_pk_mul_f32 v[164:165], v[22:23], v[164:165]
	v_pk_fma_f32 v[4:5], v[16:17], v[62:63], v[4:5] op_sel:[1,0,0]
	v_mov_b32_e32 v6, v40
	v_mov_b32_e32 v7, v56
	v_mov_b32_e32 v99, v164
	v_pk_fma_f32 v[4:5], v[20:21], v[6:7], v[4:5] op_sel_hi:[0,1,1]
	v_mov_b32_e32 v56, v41
	v_pk_add_f32 v[8:9], v[8:9], v[98:99]
	v_mul_f32_e32 v164, v23, v141
	v_pk_mul_f32 v[38:39], v[12:13], v[166:167]
	v_pk_fma_f32 v[4:5], v[20:21], v[56:57], v[4:5] op_sel:[1,0,0]
	v_mov_b32_e32 v6, v42
	v_mov_b32_e32 v7, v58
	v_pk_fma_f32 v[4:5], v[18:19], v[6:7], v[4:5] op_sel_hi:[0,1,1]
	v_pk_fma_f32 v[6:7], v[22:23], v[84:85], v[96:97] op_sel:[1,0,0]
	v_mov_b32_e32 v26, v70
	v_mov_b32_e32 v27, v86
	v_mov_b32_e32 v22, v102
	v_mov_b32_e32 v23, v118
	v_pk_add_f32 v[8:9], v[8:9], v[164:165]
	v_mov_b32_e32 v25, v38
	v_mul_f32_e32 v166, v13, v143
	v_pk_mul_f32 v[160:161], v[14:15], v[160:161]
	v_pk_fma_f32 v[6:7], v[12:13], v[26:27], v[6:7] op_sel_hi:[0,1,1]
	v_mov_b32_e32 v86, v71
	v_pk_fma_f32 v[10:11], v[12:13], v[22:23], v[10:11] op_sel_hi:[0,1,1]
	v_mov_b32_e32 v118, v103
	v_pk_add_f32 v[8:9], v[8:9], v[24:25]
	v_mov_b32_e32 v167, v39
	v_pk_fma_f32 v[6:7], v[12:13], v[86:87], v[6:7] op_sel:[1,0,0]
	v_mov_b32_e32 v26, v76
	v_mov_b32_e32 v27, v92
	v_pk_fma_f32 v[10:11], v[12:13], v[118:119], v[10:11] op_sel:[1,0,0]
	v_mov_b32_e32 v12, v108
	v_mov_b32_e32 v13, v124
	v_pk_add_f32 v[8:9], v[8:9], v[166:167]
	v_mov_b32_e32 v33, v160
	v_pk_mul_f32 v[162:163], v[16:17], v[162:163]
	v_pk_fma_f32 v[6:7], v[14:15], v[26:27], v[6:7] op_sel_hi:[0,1,1]
	v_mov_b32_e32 v92, v77
	v_pk_fma_f32 v[10:11], v[14:15], v[12:13], v[10:11] op_sel_hi:[0,1,1]
	v_mov_b32_e32 v124, v109
	v_pk_add_f32 v[8:9], v[8:9], v[32:33]
	v_mov_b32_e32 v69, v161
	v_pk_fma_f32 v[6:7], v[14:15], v[92:93], v[6:7] op_sel:[1,0,0]
	v_mov_b32_e32 v26, v78
	v_mov_b32_e32 v27, v94
	v_pk_fma_f32 v[10:11], v[14:15], v[124:125], v[10:11] op_sel:[1,0,0]
	v_mov_b32_e32 v12, v110
	v_mov_b32_e32 v13, v126
	v_pk_add_f32 v[8:9], v[8:9], v[68:69]
	v_mov_b32_e32 v35, v162
	v_mul_f32_e32 v168, v17, v139
	v_pk_fma_f32 v[6:7], v[16:17], v[26:27], v[6:7] op_sel_hi:[0,1,1]
	v_mov_b32_e32 v94, v79
	v_pk_fma_f32 v[10:11], v[16:17], v[12:13], v[10:11] op_sel_hi:[0,1,1]
	v_mov_b32_e32 v126, v111
	v_pk_add_f32 v[8:9], v[8:9], v[34:35]
	v_mov_b32_e32 v169, v163
	v_pk_fma_f32 v[6:7], v[16:17], v[94:95], v[6:7] op_sel:[1,0,0]
	v_mov_b32_e32 v26, v72
	v_mov_b32_e32 v27, v88
	v_pk_fma_f32 v[10:11], v[16:17], v[126:127], v[10:11] op_sel:[1,0,0]
	v_mov_b32_e32 v12, v104
	v_mov_b32_e32 v13, v120
	v_pk_add_f32 v[8:9], v[8:9], v[168:169]
	v_mov_b32_e32 v29, v170
	v_mul_f32_e32 v98, v21, v133
	v_pk_fma_f32 v[6:7], v[20:21], v[26:27], v[6:7] op_sel_hi:[0,1,1]
	v_mov_b32_e32 v88, v73
	v_pk_fma_f32 v[10:11], v[20:21], v[12:13], v[10:11] op_sel_hi:[0,1,1]
	v_mov_b32_e32 v120, v105
	v_pk_add_f32 v[8:9], v[8:9], v[28:29]
	v_mov_b32_e32 v99, v171
	v_pk_fma_f32 v[6:7], v[20:21], v[88:89], v[6:7] op_sel:[1,0,0]
	v_mov_b32_e32 v26, v74
	v_mov_b32_e32 v27, v90
	v_pk_fma_f32 v[10:11], v[20:21], v[120:121], v[10:11] op_sel:[1,0,0]
	v_mov_b32_e32 v12, v106
	v_mov_b32_e32 v13, v122
	v_pk_add_f32 v[8:9], v[8:9], v[98:99]
	v_mov_b32_e32 v31, v100
	v_mov_b32_e32 v58, v43
	v_pk_fma_f32 v[6:7], v[18:19], v[26:27], v[6:7] op_sel_hi:[0,1,1]
	v_mov_b32_e32 v90, v75
	v_pk_fma_f32 v[10:11], v[18:19], v[12:13], v[10:11] op_sel_hi:[0,1,1]
	v_mov_b32_e32 v122, v107
	v_mul_f32_e32 v12, v19, v135
	v_pk_add_f32 v[8:9], v[8:9], v[30:31]
	v_mov_b32_e32 v13, v101
	v_pk_fma_f32 v[4:5], v[18:19], v[58:59], v[4:5] op_sel:[1,0,0]
	v_pk_fma_f32 v[6:7], v[18:19], v[90:91], v[6:7] op_sel:[1,0,0]
	v_pk_fma_f32 v[10:11], v[18:19], v[122:123], v[10:11] op_sel:[1,0,0]
	v_pk_add_f32 v[8:9], v[8:9], v[12:13]
	s_cbranch_scc1 .LBB0_364
	s_lshl_b64 s[8:9], s[8:9], 21
	v_and_b32_e32 v12, 0x3ff, v0
	s_add_u32 s8, s6, s8
	s_addc_u32 s9, s7, s9
	v_lshlrev_b32_e32 v192, 11, v12
	v_cvt_pk_bf16_f32 v3, v6, v7
	v_lshl_add_u64 v[6:7], s[8:9], 0, v[192:193]
	s_lshl_b32 s8, s13, 1
	s_mov_b32 s9, s4
	v_lshl_add_u64 v[6:7], v[6:7], 0, s[8:9]
	s_lshl_b32 s8, s12, 1
	v_lshl_add_u64 v[6:7], v[6:7], 0, s[8:9]
	v_add_co_u32_e32 v6, vcc, 0x800000, v6
	v_add_u32_e32 v0, s34, v0
	s_nop 0
	v_addc_co_u32_e32 v7, vcc, 0, v7, vcc
	s_mov_b32 s8, 0x1ffff
	v_cmp_lt_i32_e32 vcc, s8, v0
	v_cvt_pk_bf16_f32 v2, v4, v5
	v_cvt_pk_bf16_f32 v4, v10, v11
	v_cvt_pk_bf16_f32 v5, v8, v9
	s_or_b64 s[2:3], vcc, s[2:3]
	v_subrev_u16_e32 v1, s34, v1
	flat_store_dwordx4 v[6:7], v[2:5] offset:1024
	s_andn2_b64 exec, exec, s[2:3]
	s_cbranch_execnz .LBB0_363
